# byte-phase pin: hot branch targets (K-loop heads, scan chunk latch/entry, epilogue row-loop latch) aligned to 64 bytes
# baseline (speedup 1.0000x reference)
; #define STAGE(P, BASE, br, kt) STAGET(tid_, P, BASE, br, kt)
; #define WAIT_V(n) asm volatile("s_waitcnt vmcnt(" #n ")" ::: "memory")
; #define BAR __builtin_amdgcn_s_barrier()
; template <int EPI, int K, int KL> ...
;     ...
;   if (wr == 1) BAR;
;   WAIT_V(4); BAR;
;   STAGE(SB(1, 0), Bt, bcol, 1); STAGE(SA(1, 0), A, brow, 1); STAGE(SB(1, 1), Bt, bcol + HALF, 1);
.LBB0_235:
	s_or_b64 exec, exec, s[50:51]
	v_add_u32_e32 v2, v1, v2
	v_and_b32_e32 v2, 0xfffffc00, v2
	v_sub_u32_e32 v2, v1, v2
	v_lshrrev_b32_e32 v5, 4, v2
	v_add_u32_e32 v3, v129, v3
	v_bitop3_b32 v5, v5, v2, 32 bitop3:0x6c
	v_ashrrev_i32_e32 v2, 31, v2
	v_ashrrev_i32_e32 v3, 6, v3
	v_lshrrev_b32_e32 v2, 26, v2
	v_lshlrev_b32_e32 v6, 3, v3
	v_add_u32_e32 v2, v5, v2
	v_and_b32_e32 v6, -16, v6
	v_ashrrev_i32_e32 v7, 6, v2
	v_add_u32_e32 v2, v7, v6
	v_mul_i32_i24_e32 v6, 64, v7
	s_ashr_i32 s47, s46, 31
	v_lshlrev_b32_e32 v3, 5, v3
	v_sub_u32_e32 v5, v5, v6
	s_lshl_b64 s[52:53], s[46:47], 12
	v_readlane_b32 s56, v254, 12
	v_and_b32_e32 v3, 32, v3
	v_ashrrev_i16_sdwa v5, v207, sext(v5) dst_sel:DWORD dst_unused:UNUSED_PAD src0_sel:DWORD src1_sel:BYTE_0
	v_readlane_b32 s57, v254, 13
	s_add_u32 s18, s56, s52
	v_add_u32_sdwa v130, v3, sext(v5) dst_sel:DWORD dst_unused:UNUSED_PAD src0_sel:DWORD src1_sel:WORD_0
	v_ashrrev_i32_e32 v3, 31, v2
	s_addc_u32 s19, s57, s53
	v_lshlrev_b64 v[140:141], 12, v[2:3]
	v_ashrrev_i32_e32 v131, 31, v130
	v_readlane_b32 s47, v254, 45
	v_lshl_add_u64 v[2:3], s[18:19], 0, v[140:141]
	v_lshlrev_b64 v[6:7], 1, v[130:131]
	v_add_u32_e32 v165, s47, v1
	v_lshl_add_u64 v[2:3], v[2:3], 0, v[6:7]
	s_mov_b64 s[58:59], 0x80
	v_readfirstlane_b32 s15, v165
	v_lshl_add_u64 v[2:3], v[2:3], 0, s[58:59]
	s_mov_b32 m0, s15
	s_waitcnt vmcnt(4)
	s_barrier
; #define STAGE(P, BASE, br, kt) STAGET(tid_, P, BASE, br, kt)
; #define WAIT_V(n) asm volatile("s_waitcnt vmcnt(" #n ")" ::: "memory")
; #define BAR __builtin_amdgcn_s_barrier()
; template <int EPI, int K, int KL> ...
;     ...
;   const int wid = tid_ >> 6, lane = tid_ & 63, wr = wid >> 2, wc = wid & 3, fr = lane & 15, fq = lane >> 4;
;   f32x4 acc[2][2][4][2] = {};
;   bf16x8 At[4][2], B0[2][2], B1[2][2];
;   const int nt = KL / BK;
;   if (own_prologue) {
;     STAGE(SB(0, 0), Bt, bcol, 0); STAGE(SA(0, 0), A, brow, 0);
;     STAGE(SB(0, 1), Bt, bcol + HALF, 0); STAGE(SA(0, 1), A, brow + HALF, 0);
;   }
;   if (wr == 1) BAR;
;   WAIT_V(4); BAR;
;   STAGE(SB(1, 0), Bt, bcol, 1); STAGE(SA(1, 0), A, brow, 1); STAGE(SB(1, 1), Bt, bcol + HALF, 1);
;   WAIT_V(6); BAR;
	global_load_lds_dwordx4 v[2:3], off
	v_ashrrev_i32_e32 v2, 31, v0
	v_lshrrev_b32_e32 v2, 22, v2
	v_add_u32_e32 v2, v0, v2
	v_ashrrev_i32_e32 v3, 10, v2
	v_mul_i32_i24_e32 v2, 0x400, v3
	v_sub_u32_e32 v2, v0, v2
	v_lshrrev_b32_e32 v5, 4, v2
	v_bitop3_b32 v5, v5, v2, 32 bitop3:0x6c
	v_ashrrev_i32_e32 v8, 31, v5
	v_lshrrev_b32_e32 v8, 26, v8
	v_add_u32_e32 v8, v5, v8
	v_lshlrev_b32_e32 v2, 3, v3
	v_ashrrev_i32_e32 v9, 6, v8
	v_and_b32_e32 v8, 0xc0, v8
	v_and_b32_e32 v2, -16, v2
	v_lshlrev_b32_e32 v3, 5, v3
	v_sub_u32_e32 v5, v5, v8
	v_add_u32_e32 v2, v9, v2
	v_and_b32_e32 v3, 32, v3
	v_ashrrev_i16_sdwa v5, v207, sext(v5) dst_sel:DWORD dst_unused:UNUSED_PAD src0_sel:DWORD src1_sel:BYTE_0
	v_add_u32_sdwa v142, v3, sext(v5) dst_sel:DWORD dst_unused:UNUSED_PAD src0_sel:DWORD src1_sel:WORD_0
	v_ashrrev_i32_e32 v3, 31, v2
	v_lshlrev_b64 v[144:145], 12, v[2:3]
	v_ashrrev_i32_e32 v143, 31, v142
	v_lshl_add_u64 v[2:3], s[18:19], 0, v[144:145]
	v_lshlrev_b64 v[8:9], 1, v[142:143]
	v_add_u32_e32 v5, s47, v0
	s_lshl_b64 s[18:19], s[44:45], 12
	v_lshl_add_u64 v[2:3], v[2:3], 0, v[8:9]
	v_readfirstlane_b32 s15, v5
	s_add_u32 s50, s66, s18
	v_lshl_add_u64 v[2:3], v[2:3], 0, s[58:59]
	s_mov_b32 m0, s15
	s_addc_u32 s51, s67, s19
	global_load_lds_dwordx4 v[2:3], off
	v_lshl_add_u64 v[2:3], s[50:51], 0, v[140:141]
	v_add_u32_e32 v166, 0x8000, v157
	v_lshl_add_u64 v[2:3], v[2:3], 0, v[6:7]
	v_readfirstlane_b32 s15, v166
	s_or_b32 s54, s46, 0x80
	v_lshl_add_u64 v[2:3], v[2:3], 0, s[58:59]
	s_mov_b32 m0, s15
	s_ashr_i32 s55, s54, 31
	global_load_lds_dwordx4 v[2:3], off
	v_lshl_add_u64 v[2:3], s[50:51], 0, v[144:145]
	v_add_u32_e32 v167, 0xa000, v157
	s_lshl_b64 s[54:55], s[54:55], 12
	v_lshl_add_u64 v[2:3], v[2:3], 0, v[8:9]
	v_readfirstlane_b32 s15, v167
	s_add_u32 s54, s56, s54
	v_lshl_add_u64 v[2:3], v[2:3], 0, s[58:59]
	s_mov_b32 m0, s15
	s_addc_u32 s55, s57, s55
	v_readlane_b32 s56, v254, 46
	global_load_lds_dwordx4 v[2:3], off
	v_lshl_add_u64 v[2:3], s[54:55], 0, v[140:141]
	v_add_u32_e32 v169, s56, v1
	v_lshl_add_u64 v[2:3], v[2:3], 0, v[6:7]
	v_readfirstlane_b32 s15, v169
	v_lshl_add_u64 v[2:3], v[2:3], 0, s[58:59]
	s_mov_b32 m0, s15
	v_add_u32_e32 v0, s56, v0
	global_load_lds_dwordx4 v[2:3], off
	v_lshl_add_u64 v[2:3], s[54:55], 0, v[144:145]
	v_lshl_add_u64 v[2:3], v[2:3], 0, v[8:9]
	v_readfirstlane_b32 s15, v0
	v_lshl_add_u64 v[2:3], v[2:3], 0, s[58:59]
	s_mov_b32 m0, s15
	v_and_b32_e32 v132, 15, v129
	global_load_lds_dwordx4 v[2:3], off
	v_bfe_u32 v155, v129, 4, 2
	v_lshlrev_b32_e32 v3, 2, v129
	v_lshlrev_b32_e32 v0, 4, v155
	v_lshlrev_b32_e32 v1, 6, v132
	v_and_b32_e32 v3, 32, v3
	v_bitop3_b32 v1, v0, v3, v1 bitop3:0x36
	v_readlane_b32 s15, v254, 43
	v_add_u32_e32 v11, s47, v1
	v_add_u32_e32 v12, s56, v1
	v_add_u32_e32 v5, s15, v1
	v_readlane_b32 s15, v254, 44
	v_add_u32_e32 v13, 0, v1
	v_bfe_u32 v154, v129, 6, 2
	v_add_u32_e32 v10, s15, v1
	v_lshlrev_b32_e32 v1, 6, v129
	s_movk_i32 s15, 0x3c0
	v_and_or_b32 v0, v1, s15, v0
	v_xad_u32 v3, v0, v3, 0
	v_lshl_add_u64 v[0:1], s[52:53], 0, v[140:141]
	v_lshl_add_u64 v[146:147], v[0:1], 0, v[6:7]
	v_lshl_add_u64 v[0:1], s[52:53], 0, v[144:145]
	v_lshl_add_u64 v[148:149], v[0:1], 0, v[8:9]
	v_lshl_add_u64 v[0:1], s[18:19], 0, v[140:141]
	s_waitcnt vmcnt(6)
	v_lshlrev_b32_e32 v128, 6, v4
	v_lshlrev_b32_e32 v4, 13, v4
	v_lshl_add_u64 v[150:151], v[0:1], 0, v[6:7]
	v_lshl_add_u64 v[0:1], s[18:19], 0, v[144:145]
	v_lshlrev_b32_e32 v2, 12, v154
	v_or_b32_e32 v14, 0x800, v4
	v_or_b32_e32 v15, 0x1000, v4
	v_or_b32_e32 v16, 0x1800, v4
	v_lshl_add_u64 v[152:153], v[0:1], 0, v[8:9]
	v_mov_b32_e32 v0, 0
	s_mov_b32 s15, -2
	v_add_u32_e32 v170, v5, v2
	v_add_u32_e32 v162, v13, v4
	v_add_u32_e32 v161, v3, v14
	v_add_u32_e32 v160, v3, v15
	v_add_u32_e32 v159, v3, v16
	v_add_u32_e32 v168, v10, v2
	v_add_u32_e32 v164, v11, v2
	v_add_u32_e32 v163, v12, v2
	v_mov_b32_e32 v1, v0
	v_mov_b32_e32 v2, v0
	v_mov_b32_e32 v3, v0
	v_mov_b32_e32 v4, v0
	v_mov_b32_e32 v5, v0
	v_mov_b32_e32 v6, v0
	v_mov_b32_e32 v7, v0
	v_mov_b32_e32 v8, v0
	v_mov_b32_e32 v9, v0
	v_mov_b32_e32 v10, v0
	v_mov_b32_e32 v11, v0
	v_mov_b32_e32 v12, v0
	v_mov_b32_e32 v13, v0
	v_mov_b32_e32 v14, v0
	v_mov_b32_e32 v15, v0
	v_mov_b32_e32 v16, v0
	v_mov_b32_e32 v17, v0
	v_mov_b32_e32 v18, v0
	v_mov_b32_e32 v19, v0
	v_mov_b32_e32 v20, v0
	v_mov_b32_e32 v21, v0
	v_mov_b32_e32 v22, v0
	v_mov_b32_e32 v23, v0
	v_mov_b32_e32 v24, v0
	v_mov_b32_e32 v25, v0
	v_mov_b32_e32 v26, v0
	v_mov_b32_e32 v27, v0
	v_mov_b32_e32 v28, v0
	v_mov_b32_e32 v29, v0
	v_mov_b32_e32 v30, v0
	v_mov_b32_e32 v31, v0
	v_mov_b32_e32 v32, v0
	v_mov_b32_e32 v33, v0
	v_mov_b32_e32 v34, v0
	v_mov_b32_e32 v35, v0
	v_mov_b32_e32 v36, v0
	v_mov_b32_e32 v37, v0
	v_mov_b32_e32 v38, v0
	v_mov_b32_e32 v39, v0
	v_mov_b32_e32 v40, v0
	v_mov_b32_e32 v41, v0
	v_mov_b32_e32 v42, v0
	v_mov_b32_e32 v43, v0
	v_mov_b32_e32 v44, v0
	v_mov_b32_e32 v45, v0
	v_mov_b32_e32 v46, v0
	v_mov_b32_e32 v47, v0
	v_mov_b32_e32 v48, v0
	v_mov_b32_e32 v49, v0
	v_mov_b32_e32 v50, v0
	v_mov_b32_e32 v51, v0
	v_mov_b32_e32 v52, v0
	v_mov_b32_e32 v53, v0
	v_mov_b32_e32 v54, v0
	v_mov_b32_e32 v55, v0
	v_mov_b32_e32 v56, v0
	v_mov_b32_e32 v57, v0
	v_mov_b32_e32 v58, v0
	v_mov_b32_e32 v59, v0
	v_mov_b32_e32 v60, v0
	v_mov_b32_e32 v61, v0
	v_mov_b32_e32 v62, v0
	v_mov_b32_e32 v63, v0
	v_mov_b32_e32 v64, v0
	v_mov_b32_e32 v65, v0
	v_mov_b32_e32 v66, v0
	v_mov_b32_e32 v67, v0
	v_mov_b32_e32 v68, v0
	v_mov_b32_e32 v69, v0
	v_mov_b32_e32 v70, v0
	v_mov_b32_e32 v71, v0
	v_mov_b32_e32 v72, v0
	v_mov_b32_e32 v73, v0
	v_mov_b32_e32 v74, v0
	v_mov_b32_e32 v75, v0
	v_mov_b32_e32 v76, v0
	v_mov_b32_e32 v77, v0
	v_mov_b32_e32 v78, v0
	v_mov_b32_e32 v79, v0
	v_mov_b32_e32 v80, v0
	v_mov_b32_e32 v81, v0
	v_mov_b32_e32 v82, v0
	v_mov_b32_e32 v83, v0
	v_mov_b32_e32 v84, v0
	v_mov_b32_e32 v85, v0
	v_mov_b32_e32 v86, v0
	v_mov_b32_e32 v87, v0
	v_mov_b32_e32 v88, v0
	v_mov_b32_e32 v89, v0
	v_mov_b32_e32 v90, v0
	v_mov_b32_e32 v91, v0
	v_mov_b32_e32 v92, v0
	v_mov_b32_e32 v93, v0
	v_mov_b32_e32 v94, v0
	v_mov_b32_e32 v95, v0
	v_mov_b32_e32 v96, v0
	v_mov_b32_e32 v97, v0
	v_mov_b32_e32 v98, v0
	v_mov_b32_e32 v99, v0
	v_mov_b32_e32 v100, v0
	v_mov_b32_e32 v101, v0
	v_mov_b32_e32 v102, v0
	v_mov_b32_e32 v103, v0
	v_mov_b32_e32 v104, v0
	v_mov_b32_e32 v105, v0
	v_mov_b32_e32 v106, v0
	v_mov_b32_e32 v107, v0
	v_mov_b32_e32 v108, v0
	v_mov_b32_e32 v109, v0
	v_mov_b32_e32 v110, v0
	v_mov_b32_e32 v111, v0
	v_mov_b32_e32 v112, v0
	v_mov_b32_e32 v113, v0
	v_mov_b32_e32 v114, v0
	v_mov_b32_e32 v115, v0
	v_mov_b32_e32 v116, v0
	v_mov_b32_e32 v117, v0
	v_mov_b32_e32 v118, v0
	v_mov_b32_e32 v119, v0
	v_mov_b32_e32 v120, v0
	v_mov_b32_e32 v121, v0
	v_mov_b32_e32 v122, v0
	v_mov_b32_e32 v123, v0
	v_mov_b32_e32 v124, v0
	v_mov_b32_e32 v125, v0
	v_mov_b32_e32 v126, v0
	v_mov_b32_e32 v127, v0
	s_mov_b64 s[52:53], 0x4300100
	s_mov_b64 s[54:55], 0x4380100
	s_mov_b64 s[56:57], 0x4300180
	s_mov_b64 s[58:59], 0x4380180
	.p2align 6

; #define UFOR(v, n) _Pragma("unroll") for (int v = 0; v < (n); ++v)
; __device__ __forceinline__ void phase_scan(KP p) {
;     ...
;   for (int it = bid_; it < 192; it += gridDim.x) {
;     const int rg = it & 3, dir = (it >> 2) & 1, bh = it >> 3, b = bh / 12, h = bh % 12;
;     const u16* fr_ = FA(0); const u16* fkk = FA(1); const u16* fv = FA(2);
;     const u16* fdw = FA(3 + dir); const u16* fkey = FA(5 + dir); const u16* fb = FA(7 + dir);
;     u16* Yd = Y + (size_t)dir * MT * RW;
;     f2 S01 = {0.f, 0.f}, S23 = {0.f, 0.f};
;     const int rl = lane >> 4, cs = lane & 15;
;     const int rowl = (w & 3) * 4 + rl;
;     __syncthreads();
;     const int pth = tid_ - 256, ppair = (pth >> 7) & 1, pt = pth & 127;
;     uint4 rq[2][6];
;     UFOR(x, 6) { rq[0][x] = make_uint4(0, 0, 0, 0); rq[1][x] = rq[0][x]; }
;     if (w >= 4) {
;       UFOR(e, 2) {
;         const int q = pt + 128 * e, st = q >> 3, g8 = q & 7;
;         const size_t o = (size_t)scan_row(ppair, st, b, dir) * RW + h * 64 + g8 * 8;
;         rq[e][0] = *(const uint4*)(fr_ + o); rq[e][1] = *(const uint4*)(fdw + o); rq[e][2] = *(const uint4*)(fkey + o);
;         rq[e][3] = *(const uint4*)(fkk + o); rq[e][4] = *(const uint4*)(fb + o); rq[e][5] = *(const uint4*)(fv + o);
;       }
;     }
;     for (int c = -1; c < NCH; ++c) {
.LBB0_754:
	s_or_b64 exec, exec, s[46:47]
	s_and_b32 s50, s6, 3
	s_add_u32 s48, s7, s19
	s_addc_u32 s49, s14, 0
	s_cmp_eq_u32 s18, 0
	v_readlane_b32 s18, v254, 59
	v_readlane_b32 s19, v254, 60
	s_cselect_b64 s[46:47], -1, 0
	v_lshl_add_u64 v[48:49], v[48:49], 1, s[48:49]
	s_mov_b32 s49, s19
	s_lshl_b32 s48, s50, 5
	v_writelane_b32 v254, s18, 59
	v_lshl_add_u64 v[48:49], v[48:49], 0, s[48:49]
	v_mov_b32_e32 v116, v133
	v_mov_b32_e32 v117, v133
	v_writelane_b32 v254, s19, 60
	v_lshl_add_u64 v[112:113], v[48:49], 0, v[132:133]
	s_lshl_b32 s15, s15, 14
	v_cmp_eq_u32_e64 s[48:49], s50, v124
	s_mov_b32 s18, -1
	s_mov_b64 s[68:69], -1
	v_mov_b64_e32 v[118:119], v[116:117]
	s_branch .LBB0_756
	.p2align 6

; #define UFOR(v, n) _Pragma("unroll") for (int v = 0; v < (n); ++v)
; __device__ __forceinline__ void phase_scan(KP p) {
;     ...
;         } else if (c >= 1) {
;           const int buf = (c - 1) & 1;
;           UFOR(e, 4) {
;             const int q = pt + 128 * e, st = q >> 4, rw = q & 15;
;             Yd[(size_t)scan_row(c - 1, st, b, dir) * RW + h * 64 + rg * 16 + rw] = f2bf(ybuf[(buf * 32 + st) * 16 + rw]);
;           }
;         }
;       } else if (c >= 0) {
;         const int buf = c & 1;
;         const float* fbase = feat + (buf * 32) * 320 + cs * 4;
;         const float* vb4 = vbuf + (buf * 16 + rowl) * 32;
;         const bool b3 = (cs & 8) != 0, b2 = (cs & 4) != 0;
;         float* yb = ybuf + (buf * 32 + (b3 ? 2 : 0) + (b2 ? 1 : 0)) * 16 + rowl;
;         float4 Ar, Aw, Ak, An, Ab, Br, Bw, Bk, Bn, Bb, Cr, Cw, Ck, Cn, Cb, Dr, Dw, Dk, Dn, Db;
;         float4 vcur = *(const float4*)vb4, vnext;
;         float q0 = 0.f, q1 = 0.f, q2 = 0.f, q3 = 0.f, p0 = 0.f, p1 = 0.f, p2 = 0.f, p3 = 0.f;
.LBB0_770:
	s_or_saveexec_b64 s[50:51], s[70:71]
	s_movk_i32 s71, 0x600
	s_xor_b64 exec, exec, s[50:51]
	s_cbranch_execz .LBB0_755
	s_cmp_lt_i32 s18, 0
	s_cbranch_scc1 .LBB0_755
	.p2align 6
.Lscan_entry:
	s_and_b32 s70, s18, 1
	s_cmp_lg_u32 s18, 0
	s_cbranch_scc1 .Lscan_hot
	v_and_b32_e32 v93, 63, v135
	v_bfe_u32 v94, v93, 3, 2
	v_and_b32_e32 v95, 3, v93
	v_lshl_add_u32 v94, v94, 2, v95
	v_lshrrev_b32_e32 v95, 5, v93
	v_lshl_add_u32 v94, v94, 1, v95
	s_mov_b32 s19, 0x16000
	v_lshl_add_u32 v129, v94, 4, s19
	v_and_b32_e32 v94, 15, v93
	v_lshlrev_b32_e32 v95, 3, v95
	v_sub_u32_e32 v94, v94, v95
	v_and_b32_e32 v95, 1, v94
	v_lshlrev_b32_e32 v95, 4, v95
	v_mov_b32_e32 v93, 0x3f80
	v_lshlrev_b32_e32 v93, v95, v93
	v_lshrrev_b32_e32 v94, 1, v94
	v_cmp_eq_u32_e64 s[74:75], 0, v94
	s_nop 1
	v_cndmask_b32_e64 v124, 0, v93, s[74:75]
	v_cmp_eq_u32_e64 s[74:75], 1, v94
	s_nop 1
	v_cndmask_b32_e64 v125, 0, v93, s[74:75]
	v_cmp_eq_u32_e64 s[74:75], 2, v94
	s_nop 1
	v_cndmask_b32_e64 v126, 0, v93, s[74:75]
	v_cmp_eq_u32_e64 s[74:75], 3, v94
	s_nop 1
	v_cndmask_b32_e64 v127, 0, v93, s[74:75]
	.p2align 6

; #define STAGE(P, BASE, br, kt) STAGET(tid_, P, BASE, br, kt)
; #define WAIT_V(n) asm volatile("s_waitcnt vmcnt(" #n ")" ::: "memory")
; #define BAR __builtin_amdgcn_s_barrier()
; template <int EPI, int K, int KL> ...
;     ...
;   if (wr == 1) BAR;
;   WAIT_V(4); BAR;
;   STAGE(SB(1, 0), Bt, bcol, 1); STAGE(SA(1, 0), A, brow, 1); STAGE(SB(1, 1), Bt, bcol + HALF, 1);
.LBB0_939:
	s_or_b64 exec, exec, s[58:59]
	v_add_u32_e32 v2, v1, v2
	v_and_b32_e32 v2, 0xfffffc00, v2
	v_sub_u32_e32 v2, v1, v2
	v_lshrrev_b32_e32 v5, 4, v2
	v_add_u32_e32 v3, v154, v3
	v_bitop3_b32 v5, v5, v2, 32 bitop3:0x6c
	v_ashrrev_i32_e32 v2, 31, v2
	v_ashrrev_i32_e32 v3, 6, v3
	v_lshrrev_b32_e32 v2, 26, v2
	v_lshlrev_b32_e32 v6, 3, v3
	v_add_u32_e32 v2, v5, v2
	v_and_b32_e32 v6, -16, v6
	v_ashrrev_i32_e32 v7, 6, v2
	v_add_u32_e32 v2, v7, v6
	v_mul_i32_i24_e32 v6, 64, v7
	s_ashr_i32 s55, s54, 31
	v_lshlrev_b32_e32 v3, 5, v3
	v_sub_u32_e32 v5, v5, v6
	s_lshl_b64 s[60:61], s[54:55], 12
	v_readlane_b32 s70, v254, 24
	v_and_b32_e32 v3, 32, v3
	v_ashrrev_i16_sdwa v5, v207, sext(v5) dst_sel:DWORD dst_unused:UNUSED_PAD src0_sel:DWORD src1_sel:BYTE_0
	v_readlane_b32 s71, v254, 25
	s_add_u32 s58, s70, s60
	v_add_u32_sdwa v128, v3, sext(v5) dst_sel:DWORD dst_unused:UNUSED_PAD src0_sel:DWORD src1_sel:WORD_0
	v_ashrrev_i32_e32 v3, 31, v2
	s_addc_u32 s59, s71, s61
	v_lshlrev_b64 v[130:131], 12, v[2:3]
	v_ashrrev_i32_e32 v129, 31, v128
	v_readlane_b32 s73, v254, 45
	v_lshl_add_u64 v[2:3], s[58:59], 0, v[130:131]
	v_lshlrev_b64 v[6:7], 1, v[128:129]
	v_add_u32_e32 v164, s73, v1
	v_lshl_add_u64 v[2:3], v[2:3], 0, v[6:7]
	s_mov_b64 s[74:75], 0x80
	v_readfirstlane_b32 s55, v164
	v_lshl_add_u64 v[2:3], v[2:3], 0, s[74:75]
	s_mov_b32 m0, s55
	s_waitcnt vmcnt(4)
	s_barrier
; #define STAGE(P, BASE, br, kt) STAGET(tid_, P, BASE, br, kt)
; #define WAIT_V(n) asm volatile("s_waitcnt vmcnt(" #n ")" ::: "memory")
; #define BAR __builtin_amdgcn_s_barrier()
; template <int EPI, int K, int KL> ...
;     ...
;   const int wid = tid_ >> 6, lane = tid_ & 63, wr = wid >> 2, wc = wid & 3, fr = lane & 15, fq = lane >> 4;
;   f32x4 acc[2][2][4][2] = {};
;   bf16x8 At[4][2], B0[2][2], B1[2][2];
;   const int nt = KL / BK;
;   if (own_prologue) {
;     STAGE(SB(0, 0), Bt, bcol, 0); STAGE(SA(0, 0), A, brow, 0);
;     STAGE(SB(0, 1), Bt, bcol + HALF, 0); STAGE(SA(0, 1), A, brow + HALF, 0);
;   }
;   if (wr == 1) BAR;
;   WAIT_V(4); BAR;
;   STAGE(SB(1, 0), Bt, bcol, 1); STAGE(SA(1, 0), A, brow, 1); STAGE(SB(1, 1), Bt, bcol + HALF, 1);
;   WAIT_V(6); BAR;
	global_load_lds_dwordx4 v[2:3], off
	v_ashrrev_i32_e32 v2, 31, v0
	v_lshrrev_b32_e32 v2, 22, v2
	v_add_u32_e32 v2, v0, v2
	v_ashrrev_i32_e32 v3, 10, v2
	v_mul_i32_i24_e32 v2, 0x400, v3
	v_sub_u32_e32 v2, v0, v2
	v_lshrrev_b32_e32 v5, 4, v2
	v_bitop3_b32 v5, v5, v2, 32 bitop3:0x6c
	v_ashrrev_i32_e32 v8, 31, v5
	v_lshrrev_b32_e32 v8, 26, v8
	v_add_u32_e32 v8, v5, v8
	v_lshlrev_b32_e32 v2, 3, v3
	v_ashrrev_i32_e32 v9, 6, v8
	v_and_b32_e32 v8, 0xc0, v8
	v_and_b32_e32 v2, -16, v2
	v_lshlrev_b32_e32 v3, 5, v3
	v_sub_u32_e32 v5, v5, v8
	v_add_u32_e32 v2, v9, v2
	v_and_b32_e32 v3, 32, v3
	v_ashrrev_i16_sdwa v5, v207, sext(v5) dst_sel:DWORD dst_unused:UNUSED_PAD src0_sel:DWORD src1_sel:BYTE_0
	v_add_u32_sdwa v140, v3, sext(v5) dst_sel:DWORD dst_unused:UNUSED_PAD src0_sel:DWORD src1_sel:WORD_0
	v_ashrrev_i32_e32 v3, 31, v2
	v_lshlrev_b64 v[142:143], 12, v[2:3]
	v_ashrrev_i32_e32 v141, 31, v140
	v_lshl_add_u64 v[2:3], s[58:59], 0, v[142:143]
	v_lshlrev_b64 v[8:9], 1, v[140:141]
	v_add_u32_e32 v5, s73, v0
	s_lshl_b64 s[62:63], s[52:53], 12
	v_lshl_add_u64 v[2:3], v[2:3], 0, v[8:9]
	v_readfirstlane_b32 s55, v5
	s_add_u32 s58, s66, s62
	v_lshl_add_u64 v[2:3], v[2:3], 0, s[74:75]
	s_mov_b32 m0, s55
	s_addc_u32 s59, s67, s63
	global_load_lds_dwordx4 v[2:3], off
	v_lshl_add_u64 v[2:3], s[58:59], 0, v[130:131]
	v_add_u32_e32 v166, 0x8000, v157
	v_lshl_add_u64 v[2:3], v[2:3], 0, v[6:7]
	v_readfirstlane_b32 s55, v166
	s_or_b32 s66, s54, 0x80
	v_lshl_add_u64 v[2:3], v[2:3], 0, s[74:75]
	s_mov_b32 m0, s55
	s_ashr_i32 s67, s66, 31
	global_load_lds_dwordx4 v[2:3], off
	v_lshl_add_u64 v[2:3], s[58:59], 0, v[142:143]
	v_add_u32_e32 v167, 0xa000, v157
	s_lshl_b64 s[66:67], s[66:67], 12
	v_lshl_add_u64 v[2:3], v[2:3], 0, v[8:9]
	v_readfirstlane_b32 s55, v167
	s_add_u32 s66, s70, s66
	v_lshl_add_u64 v[2:3], v[2:3], 0, s[74:75]
	s_mov_b32 m0, s55
	s_addc_u32 s67, s71, s67
	v_readlane_b32 s70, v254, 46
	global_load_lds_dwordx4 v[2:3], off
	v_lshl_add_u64 v[2:3], s[66:67], 0, v[130:131]
	v_add_u32_e32 v169, s70, v1
	v_lshl_add_u64 v[2:3], v[2:3], 0, v[6:7]
	v_readfirstlane_b32 s55, v169
	v_lshl_add_u64 v[2:3], v[2:3], 0, s[74:75]
	s_mov_b32 m0, s55
	v_add_u32_e32 v0, s70, v0
	global_load_lds_dwordx4 v[2:3], off
	v_lshl_add_u64 v[2:3], s[66:67], 0, v[142:143]
	v_lshl_add_u64 v[2:3], v[2:3], 0, v[8:9]
	v_readfirstlane_b32 s55, v0
	v_lshl_add_u64 v[2:3], v[2:3], 0, s[74:75]
	s_mov_b32 m0, s55
	v_and_b32_e32 v132, 15, v154
	global_load_lds_dwordx4 v[2:3], off
	v_bfe_u32 v153, v154, 4, 2
	v_lshlrev_b32_e32 v3, 2, v154
	v_lshlrev_b32_e32 v0, 4, v153
	v_lshlrev_b32_e32 v1, 6, v132
	v_and_b32_e32 v3, 32, v3
	v_bitop3_b32 v1, v0, v3, v1 bitop3:0x36
	v_readlane_b32 s55, v254, 43
	v_add_u32_e32 v11, s73, v1
	v_add_u32_e32 v12, s70, v1
	v_add_u32_e32 v5, s55, v1
	v_readlane_b32 s55, v254, 44
	v_add_u32_e32 v13, 0, v1
	v_bfe_u32 v152, v154, 6, 2
	v_add_u32_e32 v10, s55, v1
	v_lshlrev_b32_e32 v1, 6, v154
	s_movk_i32 s55, 0x3c0
	v_and_or_b32 v0, v1, s55, v0
	v_xad_u32 v3, v0, v3, 0
	v_lshl_add_u64 v[0:1], s[60:61], 0, v[130:131]
	v_lshl_add_u64 v[144:145], v[0:1], 0, v[6:7]
	v_lshl_add_u64 v[0:1], s[60:61], 0, v[142:143]
	v_lshl_add_u64 v[146:147], v[0:1], 0, v[8:9]
	v_lshl_add_u64 v[0:1], s[62:63], 0, v[130:131]
	s_waitcnt vmcnt(6)
	v_lshlrev_b32_e32 v155, 6, v4
	v_lshlrev_b32_e32 v4, 13, v4
	v_lshl_add_u64 v[148:149], v[0:1], 0, v[6:7]
	v_lshl_add_u64 v[0:1], s[62:63], 0, v[142:143]
	v_lshlrev_b32_e32 v2, 12, v152
	v_or_b32_e32 v14, 0x800, v4
	v_or_b32_e32 v15, 0x1000, v4
	v_or_b32_e32 v16, 0x1800, v4
	v_lshl_add_u64 v[150:151], v[0:1], 0, v[8:9]
	v_mov_b32_e32 v0, 0
	s_mov_b32 s55, -2
	v_add_u32_e32 v170, v5, v2
	v_add_u32_e32 v162, v13, v4
	v_add_u32_e32 v161, v3, v14
	v_add_u32_e32 v160, v3, v15
	v_add_u32_e32 v159, v3, v16
	v_add_u32_e32 v168, v10, v2
	v_add_u32_e32 v165, v11, v2
	v_add_u32_e32 v163, v12, v2
	v_mov_b32_e32 v1, v0
	v_mov_b32_e32 v2, v0
	v_mov_b32_e32 v3, v0
	v_mov_b32_e32 v4, v0
	v_mov_b32_e32 v5, v0
	v_mov_b32_e32 v6, v0
	v_mov_b32_e32 v7, v0
	v_mov_b32_e32 v8, v0
	v_mov_b32_e32 v9, v0
	v_mov_b32_e32 v10, v0
	v_mov_b32_e32 v11, v0
	v_mov_b32_e32 v12, v0
	v_mov_b32_e32 v13, v0
	v_mov_b32_e32 v14, v0
	v_mov_b32_e32 v15, v0
	v_mov_b32_e32 v16, v0
	v_mov_b32_e32 v17, v0
	v_mov_b32_e32 v18, v0
	v_mov_b32_e32 v19, v0
	v_mov_b32_e32 v20, v0
	v_mov_b32_e32 v21, v0
	v_mov_b32_e32 v22, v0
	v_mov_b32_e32 v23, v0
	v_mov_b32_e32 v24, v0
	v_mov_b32_e32 v25, v0
	v_mov_b32_e32 v26, v0
	v_mov_b32_e32 v27, v0
	v_mov_b32_e32 v28, v0
	v_mov_b32_e32 v29, v0
	v_mov_b32_e32 v30, v0
	v_mov_b32_e32 v31, v0
	v_mov_b32_e32 v32, v0
	v_mov_b32_e32 v33, v0
	v_mov_b32_e32 v34, v0
	v_mov_b32_e32 v35, v0
	v_mov_b32_e32 v36, v0
	v_mov_b32_e32 v37, v0
	v_mov_b32_e32 v38, v0
	v_mov_b32_e32 v39, v0
	v_mov_b32_e32 v40, v0
	v_mov_b32_e32 v41, v0
	v_mov_b32_e32 v42, v0
	v_mov_b32_e32 v43, v0
	v_mov_b32_e32 v44, v0
	v_mov_b32_e32 v45, v0
	v_mov_b32_e32 v46, v0
	v_mov_b32_e32 v47, v0
	v_mov_b32_e32 v48, v0
	v_mov_b32_e32 v49, v0
	v_mov_b32_e32 v50, v0
	v_mov_b32_e32 v51, v0
	v_mov_b32_e32 v52, v0
	v_mov_b32_e32 v53, v0
	v_mov_b32_e32 v54, v0
	v_mov_b32_e32 v55, v0
	v_mov_b32_e32 v56, v0
	v_mov_b32_e32 v57, v0
	v_mov_b32_e32 v58, v0
	v_mov_b32_e32 v59, v0
	v_mov_b32_e32 v60, v0
	v_mov_b32_e32 v61, v0
	v_mov_b32_e32 v62, v0
	v_mov_b32_e32 v63, v0
	v_mov_b32_e32 v64, v0
	v_mov_b32_e32 v65, v0
	v_mov_b32_e32 v66, v0
	v_mov_b32_e32 v67, v0
	v_mov_b32_e32 v68, v0
	v_mov_b32_e32 v69, v0
	v_mov_b32_e32 v70, v0
	v_mov_b32_e32 v71, v0
	v_mov_b32_e32 v72, v0
	v_mov_b32_e32 v73, v0
	v_mov_b32_e32 v74, v0
	v_mov_b32_e32 v75, v0
	v_mov_b32_e32 v76, v0
	v_mov_b32_e32 v77, v0
	v_mov_b32_e32 v78, v0
	v_mov_b32_e32 v79, v0
	v_mov_b32_e32 v80, v0
	v_mov_b32_e32 v81, v0
	v_mov_b32_e32 v82, v0
	v_mov_b32_e32 v83, v0
	v_mov_b32_e32 v84, v0
	v_mov_b32_e32 v85, v0
	v_mov_b32_e32 v86, v0
	v_mov_b32_e32 v87, v0
	v_mov_b32_e32 v88, v0
	v_mov_b32_e32 v89, v0
	v_mov_b32_e32 v90, v0
	v_mov_b32_e32 v91, v0
	v_mov_b32_e32 v92, v0
	v_mov_b32_e32 v93, v0
	v_mov_b32_e32 v94, v0
	v_mov_b32_e32 v95, v0
	v_mov_b32_e32 v96, v0
	v_mov_b32_e32 v97, v0
	v_mov_b32_e32 v98, v0
	v_mov_b32_e32 v99, v0
	v_mov_b32_e32 v100, v0
	v_mov_b32_e32 v101, v0
	v_mov_b32_e32 v102, v0
	v_mov_b32_e32 v103, v0
	v_mov_b32_e32 v104, v0
	v_mov_b32_e32 v105, v0
	v_mov_b32_e32 v106, v0
	v_mov_b32_e32 v107, v0
	v_mov_b32_e32 v108, v0
	v_mov_b32_e32 v109, v0
	v_mov_b32_e32 v110, v0
	v_mov_b32_e32 v111, v0
	v_mov_b32_e32 v112, v0
	v_mov_b32_e32 v113, v0
	v_mov_b32_e32 v114, v0
	v_mov_b32_e32 v115, v0
	v_mov_b32_e32 v116, v0
	v_mov_b32_e32 v117, v0
	v_mov_b32_e32 v118, v0
	v_mov_b32_e32 v119, v0
	v_mov_b32_e32 v120, v0
	v_mov_b32_e32 v121, v0
	v_mov_b32_e32 v122, v0
	v_mov_b32_e32 v123, v0
	v_mov_b32_e32 v124, v0
	v_mov_b32_e32 v125, v0
	v_mov_b32_e32 v126, v0
	v_mov_b32_e32 v127, v0
	s_mov_b64 s[62:63], 0x5f00100
	s_mov_b64 s[66:67], 0x5f80100
	s_mov_b64 s[70:71], 0x5f00180
	s_mov_b64 s[74:75], 0x5f80180
	.p2align 6

; #define STAGE(P, BASE, br, kt) STAGET(tid_, P, BASE, br, kt)
; #define WAIT_V(n) asm volatile("s_waitcnt vmcnt(" #n ")" ::: "memory")
; #define BAR __builtin_amdgcn_s_barrier()
; template <int EPI, int K, int KL> ...
;     ...
;   if (wr == 1) BAR;
;   WAIT_V(4); BAR;
;   STAGE(SB(1, 0), Bt, bcol, 1); STAGE(SA(1, 0), A, brow, 1); STAGE(SB(1, 1), Bt, bcol + HALF, 1);
.LBB0_1106:
	s_or_b64 exec, exec, s[40:41]
	v_add_u32_e32 v2, v1, v2
	v_and_b32_e32 v2, 0xfffffc00, v2
	v_sub_u32_e32 v2, v1, v2
	s_waitcnt vmcnt(0)
	v_lshrrev_b32_e32 v4, 4, v2
	v_add_u32_e32 v3, v152, v3
	v_bitop3_b32 v4, v4, v2, 32 bitop3:0x6c
	v_ashrrev_i32_e32 v2, 31, v2
	v_ashrrev_i32_e32 v3, 6, v3
	v_lshrrev_b32_e32 v2, 26, v2
	v_lshlrev_b32_e32 v5, 3, v3
	v_add_u32_e32 v2, v4, v2
	v_and_b32_e32 v5, -16, v5
	v_ashrrev_i32_e32 v6, 6, v2
	v_add_u32_e32 v2, v6, v5
	v_mul_i32_i24_e32 v5, 64, v6
	s_ashr_i32 s57, s56, 31
	v_lshlrev_b32_e32 v3, 5, v3
	v_sub_u32_e32 v4, v4, v5
	s_lshl_b64 s[58:59], s[56:57], 12
	v_readlane_b32 s70, v254, 20
	v_and_b32_e32 v3, 32, v3
	v_ashrrev_i16_sdwa v4, v207, sext(v4) dst_sel:DWORD dst_unused:UNUSED_PAD src0_sel:DWORD src1_sel:BYTE_0
	v_readlane_b32 s71, v254, 21
	s_add_u32 s40, s70, s58
	v_add_u32_sdwa v128, v3, sext(v4) dst_sel:DWORD dst_unused:UNUSED_PAD src0_sel:DWORD src1_sel:WORD_0
	v_ashrrev_i32_e32 v3, 31, v2
	s_addc_u32 s41, s71, s59
	v_lshlrev_b64 v[130:131], 12, v[2:3]
	v_ashrrev_i32_e32 v129, 31, v128
	v_readlane_b32 s61, v254, 45
	v_lshl_add_u64 v[2:3], s[40:41], 0, v[130:131]
	v_lshlrev_b64 v[4:5], 1, v[128:129]
	v_add_u32_e32 v165, s61, v1
	v_lshl_add_u64 v[2:3], v[2:3], 0, v[4:5]
	s_mov_b64 s[74:75], 0x80
	v_readfirstlane_b32 s53, v165
	v_lshl_add_u64 v[2:3], v[2:3], 0, s[74:75]
	s_mov_b32 m0, s53
	s_waitcnt vmcnt(4)
	s_barrier
; #define STAGE(P, BASE, br, kt) STAGET(tid_, P, BASE, br, kt)
; #define WAIT_V(n) asm volatile("s_waitcnt vmcnt(" #n ")" ::: "memory")
; #define BAR __builtin_amdgcn_s_barrier()
; template <int EPI, int K, int KL> ...
;     ...
;   const int wid = tid_ >> 6, lane = tid_ & 63, wr = wid >> 2, wc = wid & 3, fr = lane & 15, fq = lane >> 4;
;   f32x4 acc[2][2][4][2] = {};
;   bf16x8 At[4][2], B0[2][2], B1[2][2];
;   const int nt = KL / BK;
;   if (own_prologue) {
;     STAGE(SB(0, 0), Bt, bcol, 0); STAGE(SA(0, 0), A, brow, 0);
;     STAGE(SB(0, 1), Bt, bcol + HALF, 0); STAGE(SA(0, 1), A, brow + HALF, 0);
;   }
;   if (wr == 1) BAR;
;   WAIT_V(4); BAR;
;   STAGE(SB(1, 0), Bt, bcol, 1); STAGE(SA(1, 0), A, brow, 1); STAGE(SB(1, 1), Bt, bcol + HALF, 1);
;   WAIT_V(6); BAR;
	global_load_lds_dwordx4 v[2:3], off
	v_ashrrev_i32_e32 v2, 31, v0
	v_lshrrev_b32_e32 v2, 22, v2
	v_add_u32_e32 v2, v0, v2
	v_ashrrev_i32_e32 v3, 10, v2
	v_mul_i32_i24_e32 v2, 0x400, v3
	v_sub_u32_e32 v2, v0, v2
	v_lshrrev_b32_e32 v6, 4, v2
	v_bitop3_b32 v6, v6, v2, 32 bitop3:0x6c
	v_ashrrev_i32_e32 v7, 31, v6
	v_lshrrev_b32_e32 v7, 26, v7
	v_add_u32_e32 v7, v6, v7
	v_lshlrev_b32_e32 v2, 3, v3
	v_ashrrev_i32_e32 v8, 6, v7
	v_and_b32_e32 v7, 0xc0, v7
	v_and_b32_e32 v2, -16, v2
	v_lshlrev_b32_e32 v3, 5, v3
	v_sub_u32_e32 v6, v6, v7
	v_add_u32_e32 v2, v8, v2
	v_and_b32_e32 v3, 32, v3
	v_ashrrev_i16_sdwa v6, v207, sext(v6) dst_sel:DWORD dst_unused:UNUSED_PAD src0_sel:DWORD src1_sel:BYTE_0
	v_add_u32_sdwa v140, v3, sext(v6) dst_sel:DWORD dst_unused:UNUSED_PAD src0_sel:DWORD src1_sel:WORD_0
	v_ashrrev_i32_e32 v3, 31, v2
	v_lshlrev_b64 v[142:143], 12, v[2:3]
	v_ashrrev_i32_e32 v141, 31, v140
	v_add_u32_e32 v8, s61, v0
	v_lshl_add_u64 v[2:3], s[40:41], 0, v[142:143]
	v_lshlrev_b64 v[6:7], 1, v[140:141]
	v_readfirstlane_b32 s40, v8
	s_lshl_b64 s[62:63], s[42:43], 12
	v_lshl_add_u64 v[2:3], v[2:3], 0, v[6:7]
	s_mov_b32 m0, s40
	s_add_u32 s40, s66, s62
	v_lshl_add_u64 v[2:3], v[2:3], 0, s[74:75]
	s_addc_u32 s41, s67, s63
	global_load_lds_dwordx4 v[2:3], off
	v_lshl_add_u64 v[2:3], s[40:41], 0, v[130:131]
	v_add_u32_e32 v167, 0x8000, v158
	v_lshl_add_u64 v[2:3], v[2:3], 0, v[4:5]
	v_readfirstlane_b32 s53, v167
	s_bitset1_b32 s56, 7
	v_lshl_add_u64 v[2:3], v[2:3], 0, s[74:75]
	s_mov_b32 m0, s53
	s_ashr_i32 s57, s56, 31
	global_load_lds_dwordx4 v[2:3], off
	v_lshl_add_u64 v[2:3], s[40:41], 0, v[142:143]
	v_add_u32_e32 v168, 0xa000, v158
	s_lshl_b64 s[56:57], s[56:57], 12
	v_lshl_add_u64 v[2:3], v[2:3], 0, v[6:7]
	v_readfirstlane_b32 s53, v168
	s_add_u32 s56, s70, s56
	v_lshl_add_u64 v[2:3], v[2:3], 0, s[74:75]
	s_mov_b32 m0, s53
	s_addc_u32 s57, s71, s57
	v_readlane_b32 s70, v254, 46
	global_load_lds_dwordx4 v[2:3], off
	v_lshl_add_u64 v[2:3], s[56:57], 0, v[130:131]
	v_add_u32_e32 v170, s70, v1
	v_lshl_add_u64 v[2:3], v[2:3], 0, v[4:5]
	v_readfirstlane_b32 s53, v170
	v_lshl_add_u64 v[2:3], v[2:3], 0, s[74:75]
	s_mov_b32 m0, s53
	v_add_u32_e32 v0, s70, v0
	global_load_lds_dwordx4 v[2:3], off
	v_lshl_add_u64 v[2:3], s[56:57], 0, v[142:143]
	v_lshl_add_u64 v[2:3], v[2:3], 0, v[6:7]
	v_readfirstlane_b32 s53, v0
	v_lshl_add_u64 v[2:3], v[2:3], 0, s[74:75]
	s_mov_b32 m0, s53
	v_and_b32_e32 v154, 15, v152
	global_load_lds_dwordx4 v[2:3], off
	v_lshlrev_b32_e32 v132, 2, v152
	v_and_b32_e32 v156, 48, v152
	v_lshlrev_b32_e32 v0, 6, v154
	v_and_b32_e32 v1, 32, v132
	v_bitop3_b32 v0, v0, v1, v156 bitop3:0x36
	v_readlane_b32 s53, v254, 43
	v_add_u32_e32 v9, s61, v0
	v_add_u32_e32 v10, s70, v0
	v_add_u32_e32 v3, s53, v0
	v_readlane_b32 s53, v254, 44
	v_add_u32_e32 v12, 0, v0
	v_bfe_u32 v155, v152, 6, 2
	v_add_u32_e32 v8, s53, v0
	v_lshlrev_b32_e32 v0, 6, v152
	s_movk_i32 s53, 0x3c0
	v_and_or_b32 v0, v0, s53, v156
	v_xad_u32 v13, v0, v1, 0
	v_lshl_add_u64 v[0:1], s[58:59], 0, v[130:131]
	v_lshl_add_u64 v[144:145], v[0:1], 0, v[4:5]
	v_lshl_add_u64 v[0:1], s[58:59], 0, v[142:143]
	v_lshl_add_u64 v[146:147], v[0:1], 0, v[6:7]
	v_lshl_add_u64 v[0:1], s[62:63], 0, v[130:131]
	s_waitcnt vmcnt(6)
	v_lshlrev_b32_e32 v11, 13, v153
	v_lshl_add_u64 v[148:149], v[0:1], 0, v[4:5]
	v_lshl_add_u64 v[0:1], s[62:63], 0, v[142:143]
	v_lshlrev_b32_e32 v2, 12, v155
	v_or_b32_e32 v14, 0x800, v11
	v_or_b32_e32 v15, 0x1000, v11
	v_or_b32_e32 v16, 0x1800, v11
	v_lshl_add_u64 v[150:151], v[0:1], 0, v[6:7]
	v_mov_b32_e32 v0, 0
	s_mov_b32 s53, -2
	v_add_u32_e32 v171, v3, v2
	v_add_u32_e32 v163, v12, v11
	v_add_u32_e32 v162, v13, v14
	v_add_u32_e32 v161, v13, v15
	v_add_u32_e32 v160, v13, v16
	v_add_u32_e32 v169, v8, v2
	v_add_u32_e32 v166, v9, v2
	v_add_u32_e32 v164, v10, v2
	v_mov_b32_e32 v1, v0
	v_mov_b32_e32 v2, v0
	v_mov_b32_e32 v3, v0
	v_mov_b32_e32 v4, v0
	v_mov_b32_e32 v5, v0
	v_mov_b32_e32 v6, v0
	v_mov_b32_e32 v7, v0
	v_mov_b32_e32 v8, v0
	v_mov_b32_e32 v9, v0
	v_mov_b32_e32 v10, v0
	v_mov_b32_e32 v11, v0
	v_mov_b32_e32 v16, v0
	v_mov_b32_e32 v17, v0
	v_mov_b32_e32 v18, v0
	v_mov_b32_e32 v19, v0
	v_mov_b32_e32 v28, v0
	v_mov_b32_e32 v29, v0
	v_mov_b32_e32 v30, v0
	v_mov_b32_e32 v31, v0
	v_mov_b32_e32 v40, v0
	v_mov_b32_e32 v41, v0
	v_mov_b32_e32 v42, v0
	v_mov_b32_e32 v43, v0
	v_mov_b32_e32 v52, v0
	v_mov_b32_e32 v53, v0
	v_mov_b32_e32 v54, v0
	v_mov_b32_e32 v55, v0
	v_mov_b32_e32 v64, v0
	v_mov_b32_e32 v65, v0
	v_mov_b32_e32 v66, v0
	v_mov_b32_e32 v67, v0
	v_mov_b32_e32 v12, v0
	v_mov_b32_e32 v13, v0
	v_mov_b32_e32 v14, v0
	v_mov_b32_e32 v15, v0
	v_mov_b32_e32 v24, v0
	v_mov_b32_e32 v25, v0
	v_mov_b32_e32 v26, v0
	v_mov_b32_e32 v27, v0
	v_mov_b32_e32 v36, v0
	v_mov_b32_e32 v37, v0
	v_mov_b32_e32 v38, v0
	v_mov_b32_e32 v39, v0
	v_mov_b32_e32 v48, v0
	v_mov_b32_e32 v49, v0
	v_mov_b32_e32 v50, v0
	v_mov_b32_e32 v51, v0
	v_mov_b32_e32 v60, v0
	v_mov_b32_e32 v61, v0
	v_mov_b32_e32 v62, v0
	v_mov_b32_e32 v63, v0
	v_mov_b32_e32 v72, v0
	v_mov_b32_e32 v73, v0
	v_mov_b32_e32 v74, v0
	v_mov_b32_e32 v75, v0
	v_mov_b32_e32 v80, v0
	v_mov_b32_e32 v81, v0
	v_mov_b32_e32 v82, v0
	v_mov_b32_e32 v83, v0
	v_mov_b32_e32 v88, v0
	v_mov_b32_e32 v89, v0
	v_mov_b32_e32 v90, v0
	v_mov_b32_e32 v91, v0
	v_mov_b32_e32 v20, v0
	v_mov_b32_e32 v21, v0
	v_mov_b32_e32 v22, v0
	v_mov_b32_e32 v23, v0
	v_mov_b32_e32 v32, v0
	v_mov_b32_e32 v33, v0
	v_mov_b32_e32 v34, v0
	v_mov_b32_e32 v35, v0
	v_mov_b32_e32 v44, v0
	v_mov_b32_e32 v45, v0
	v_mov_b32_e32 v46, v0
	v_mov_b32_e32 v47, v0
	v_mov_b32_e32 v56, v0
	v_mov_b32_e32 v57, v0
	v_mov_b32_e32 v58, v0
	v_mov_b32_e32 v59, v0
	v_mov_b32_e32 v68, v0
	v_mov_b32_e32 v69, v0
	v_mov_b32_e32 v70, v0
	v_mov_b32_e32 v71, v0
	v_mov_b32_e32 v76, v0
	v_mov_b32_e32 v77, v0
	v_mov_b32_e32 v78, v0
	v_mov_b32_e32 v79, v0
	v_mov_b32_e32 v84, v0
	v_mov_b32_e32 v85, v0
	v_mov_b32_e32 v86, v0
	v_mov_b32_e32 v87, v0
	v_mov_b32_e32 v92, v0
	v_mov_b32_e32 v93, v0
	v_mov_b32_e32 v94, v0
	v_mov_b32_e32 v95, v0
	v_mov_b32_e32 v96, v0
	v_mov_b32_e32 v97, v0
	v_mov_b32_e32 v98, v0
	v_mov_b32_e32 v99, v0
	v_mov_b32_e32 v100, v0
	v_mov_b32_e32 v101, v0
	v_mov_b32_e32 v102, v0
	v_mov_b32_e32 v103, v0
	v_mov_b32_e32 v104, v0
	v_mov_b32_e32 v105, v0
	v_mov_b32_e32 v106, v0
	v_mov_b32_e32 v107, v0
	v_mov_b32_e32 v108, v0
	v_mov_b32_e32 v109, v0
	v_mov_b32_e32 v110, v0
	v_mov_b32_e32 v111, v0
	v_mov_b32_e32 v112, v0
	v_mov_b32_e32 v113, v0
	v_mov_b32_e32 v114, v0
	v_mov_b32_e32 v115, v0
	v_mov_b32_e32 v116, v0
	v_mov_b32_e32 v117, v0
	v_mov_b32_e32 v118, v0
	v_mov_b32_e32 v119, v0
	v_mov_b32_e32 v120, v0
	v_mov_b32_e32 v121, v0
	v_mov_b32_e32 v122, v0
	v_mov_b32_e32 v123, v0
	v_mov_b32_e32 v124, v0
	v_mov_b32_e32 v125, v0
	v_mov_b32_e32 v126, v0
	v_mov_b32_e32 v127, v0
	.p2align 6

; #define UFOR(v, n) _Pragma("unroll") for (int v = 0; v < (n); ++v)
; #define LDS_BARRIER() do { asm volatile("s_waitcnt lgkmcnt(0)" ::: "memory"); __builtin_amdgcn_s_barrier(); asm volatile("" ::: "memory"); } while (0)
; __device__ __forceinline__ unsigned pk2(float a, float b) { return (unsigned)f2bf(a) | ((unsigned)f2bf(b) << 16); }
; __device__ __forceinline__ float lo2f(unsigned u) { return __uint_as_float(u << 16); }
; __device__ __forceinline__ float hi2f(unsigned u) { return __uint_as_float(u & 0xffff0000u); }
; template <int EPI, int K, int KL> ...
;     ...
;     u16* U = (u16*)smem;
;     LDS_BARRIER();
;     UFOR(ai, 2) UFOR(bj, 2) UFOR(m, 4) {
;       const f32x4 a = acc[ai][bj][m][0], b = acc[ai][bj][m][1];
;       uint4 pk; pk.x = pk2(a[0], a[1]); pk.y = pk2(a[2], a[3]); pk.z = pk2(b[0], b[1]); pk.w = pk2(b[2], b[3]);
;       *(uint4*)(U + (ai * HALF + wr * 64 + m * 16 + fr) * 256 + bj * 128 + wc * 32 + fq * 8) = pk;
;     }
;     LDS_BARRIER();
;     {
;       const int c4 = (tid_ & 31) * 4, rb = tid_ >> 5;
;       const int gc = pn * 128 + c4;
;       float wg[4][3], wv[4][3];
;       UFOR(q, 4) UFOR(x, 3) { wg[q][x] = e.cw[(size_t)(gc + q) * 3 + x]; wv[q][x] = e.cw[(size_t)(DFF + gc + q) * 3 + x]; }
;       float pg[4], cgv[4], ng[4], pvv[4], cv[4], nv[4];
;       const int lr0 = rb * 16;
;       {
;         const int lrp = lr0 > 0 ? lr0 - 1 : 0;
;         const uint2 a = *(const uint2*)(U + lrp * 256 + c4), b = *(const uint2*)(U + lrp * 256 + 128 + c4);
;         pg[0] = lo2f(a.x); pg[1] = hi2f(a.x); pg[2] = lo2f(a.y); pg[3] = hi2f(a.y);
;         pvv[0] = lo2f(b.x); pvv[1] = hi2f(b.x); pvv[2] = lo2f(b.y); pvv[3] = hi2f(b.y);
;         const uint2 c = *(const uint2*)(U + lr0 * 256 + c4), d = *(const uint2*)(U + lr0 * 256 + 128 + c4);
;         cgv[0] = lo2f(c.x); cgv[1] = hi2f(c.x); cgv[2] = lo2f(c.y); cgv[3] = hi2f(c.y);
;         cv[0] = lo2f(d.x); cv[1] = hi2f(d.x); cv[2] = lo2f(d.y); cv[3] = hi2f(d.y);
;       }
; #pragma unroll 2
;       for (int q = 0; q < 16; ++q) {
;         const int lr = lr0 + q;
;         const int lrn = lr < 255 ? lr + 1 : 255;
;         const uint2 a = *(const uint2*)(U + lrn * 256 + c4), b = *(const uint2*)(U + lrn * 256 + 128 + c4);
.LBB0_1110:
	s_or_b64 exec, exec, s[40:41]
	v_bfe_u32 v128, v152, 4, 4
	v_xor_b32_e32 v128, v128, v154
	v_lshlrev_b32_e32 v128, 4, v128
	v_lshlrev_b32_e32 v129, 15, v153
	v_lshlrev_b32_e32 v130, 9, v154
	v_add3_u32 v128, v128, v129, v130
	v_cvt_pk_bf16_f32 v124, v124, v125
	v_cvt_pk_bf16_f32 v125, v126, v127
	v_cvt_pk_bf16_f32 v126, v120, v121
	v_cvt_pk_bf16_f32 v116, v116, v117
	v_cvt_pk_bf16_f32 v117, v118, v119
	v_cvt_pk_bf16_f32 v118, v112, v113
	v_cvt_pk_bf16_f32 v108, v108, v109
	v_cvt_pk_bf16_f32 v109, v110, v111
	v_cvt_pk_bf16_f32 v110, v104, v105
	v_cvt_pk_bf16_f32 v100, v100, v101
	v_cvt_pk_bf16_f32 v101, v102, v103
	v_cvt_pk_bf16_f32 v102, v96, v97
	v_cvt_pk_bf16_f32 v92, v92, v93
	v_cvt_pk_bf16_f32 v93, v94, v95
	v_cvt_pk_bf16_f32 v94, v88, v89
	v_cvt_pk_bf16_f32 v84, v84, v85
	v_cvt_pk_bf16_f32 v85, v86, v87
	v_cvt_pk_bf16_f32 v86, v80, v81
	v_cvt_pk_bf16_f32 v76, v76, v77
	v_cvt_pk_bf16_f32 v77, v78, v79
	v_cvt_pk_bf16_f32 v78, v72, v73
	v_cvt_pk_bf16_f32 v68, v68, v69
	v_cvt_pk_bf16_f32 v69, v70, v71
	v_cvt_pk_bf16_f32 v70, v64, v65
	v_cvt_pk_bf16_f32 v71, v66, v67
	v_cvt_pk_bf16_f32 v60, v60, v61
	v_cvt_pk_bf16_f32 v61, v62, v63
	v_cvt_pk_bf16_f32 v62, v56, v57
	v_cvt_pk_bf16_f32 v63, v58, v59
	v_cvt_pk_bf16_f32 v52, v52, v53
	v_cvt_pk_bf16_f32 v53, v54, v55
	v_cvt_pk_bf16_f32 v54, v48, v49
	v_cvt_pk_bf16_f32 v55, v50, v51
	v_cvt_pk_bf16_f32 v44, v44, v45
	v_cvt_pk_bf16_f32 v45, v46, v47
	v_cvt_pk_bf16_f32 v46, v40, v41
	v_cvt_pk_bf16_f32 v47, v42, v43
	v_cvt_pk_bf16_f32 v36, v36, v37
	v_cvt_pk_bf16_f32 v37, v38, v39
	v_cvt_pk_bf16_f32 v38, v32, v33
	v_cvt_pk_bf16_f32 v39, v34, v35
	v_cvt_pk_bf16_f32 v28, v28, v29
	v_cvt_pk_bf16_f32 v29, v30, v31
	v_cvt_pk_bf16_f32 v30, v24, v25
	v_cvt_pk_bf16_f32 v31, v26, v27
	v_cvt_pk_bf16_f32 v20, v20, v21
	v_cvt_pk_bf16_f32 v21, v22, v23
	v_cvt_pk_bf16_f32 v22, v16, v17
	v_cvt_pk_bf16_f32 v23, v18, v19
	v_cvt_pk_bf16_f32 v12, v12, v13
	v_cvt_pk_bf16_f32 v13, v14, v15
	v_cvt_pk_bf16_f32 v14, v8, v9
	v_cvt_pk_bf16_f32 v15, v10, v11
	v_cvt_pk_bf16_f32 v4, v4, v5
	v_cvt_pk_bf16_f32 v5, v6, v7
	v_cvt_pk_bf16_f32 v127, v122, v123
	v_cvt_pk_bf16_f32 v119, v114, v115
	v_cvt_pk_bf16_f32 v111, v106, v107
	v_cvt_pk_bf16_f32 v103, v98, v99
	v_cvt_pk_bf16_f32 v95, v90, v91
	v_cvt_pk_bf16_f32 v87, v82, v83
	v_cvt_pk_bf16_f32 v79, v74, v75
	v_cvt_pk_bf16_f32 v7, v2, v3
	v_cvt_pk_bf16_f32 v6, v0, v1
	v_add_u32_e32 v16, 0x14100, v128
	s_waitcnt lgkmcnt(0)
	s_barrier
	v_add_u32_e32 v32, 0x10100, v128
	ds_write_b128 v16, v[12:15]
	v_and_b32_e32 v16, 0x7c, v132
	v_add_u32_e32 v64, 0x10000, v128
	v_add_u32_e32 v56, 0x12000, v128
	v_add_u32_e32 v48, 0x14000, v128
	v_add_u32_e32 v40, 0x16000, v128
	ds_write_b128 v32, v[28:31]
	v_add_u32_e32 v24, 0x12100, v128
	v_add_u32_e32 v8, 0x16100, v128
	v_lshl_or_b32 v32, s51, 7, v16
	ds_write_b128 v128, v[124:127]
	ds_write_b128 v128, v[116:119] offset:8192
	ds_write_b128 v128, v[108:111] offset:16384
	ds_write_b128 v128, v[100:103] offset:24576
	ds_write_b128 v128, v[92:95] offset:256
	ds_write_b128 v128, v[84:87] offset:8448
	ds_write_b128 v128, v[76:79] offset:16640
	ds_write_b128 v128, v[68:71] offset:24832
	ds_write_b128 v64, v[60:63]
	ds_write_b128 v56, v[52:55]
	ds_write_b128 v48, v[44:47]
	ds_write_b128 v40, v[36:39]
	ds_write_b128 v24, v[20:23]
	ds_write_b128 v8, v[4:7]
	v_add_u32_e32 v0, 0x1600, v32
	s_waitcnt lgkmcnt(0)
	s_barrier
	s_waitcnt vmcnt(0)
	v_mov_b32_e32 v24, v218
	v_mov_b32_e32 v25, v219
	v_mov_b32_e32 v26, v220
	v_mov_b32_e32 v27, v221
	v_mov_b32_e32 v0, v222
	v_mov_b32_e32 v1, v223
	v_mov_b32_e32 v2, v224
	v_mov_b32_e32 v3, v225
	v_mov_b32_e32 v4, v226
	v_mov_b32_e32 v5, v227
	v_mov_b32_e32 v6, v228
	v_mov_b32_e32 v7, v229
	v_mov_b32_e32 v8, v230
	v_mov_b32_e32 v9, v231
	v_mov_b32_e32 v10, v232
	v_mov_b32_e32 v11, v233
	v_mov_b32_e32 v28, v234
	v_mov_b32_e32 v29, v235
	v_mov_b32_e32 v30, v236
	v_mov_b32_e32 v31, v237
	v_mov_b32_e32 v12, v238
	v_mov_b32_e32 v13, v239
	v_mov_b32_e32 v14, v240
	v_mov_b32_e32 v15, v241
	v_ashrrev_i32_e32 v34, 1, v152
	v_and_b32_e32 v132, -16, v34
	v_mov_b32_e32 v17, 0xffffff00
	v_lshl_add_u32 v17, v132, 8, v17
	v_cmp_lt_i32_e32 vcc, 15, v34
	v_lshl_add_u32 v64, v16, 1, 0
	v_bfe_u32 v96, v152, 1, 4
	v_and_b32_e32 v97, 1, v152
	v_lshlrev_b32_e32 v97, 3, v97
	s_ashr_i32 s51, s50, 31
	v_cndmask_b32_e32 v17, 0, v17, vcc
	v_lshrrev_b32_e32 v98, 8, v17
	v_and_b32_e32 v98, 15, v98
	v_xor_b32_e32 v98, v98, v96
	v_lshl_add_u32 v98, v98, 4, v97
	v_lshl_add_u32 v16, v17, 1, v98
	ds_read2_b64 v[16:19], v16 offset1:32
	s_ashr_i32 s53, s52, 31
	s_add_u32 s56, s52, -1
	s_addc_u32 s57, s53, -1
	s_add_i32 s61, s52, -1
	s_waitcnt lgkmcnt(0)
	v_and_b32_e32 v56, 0xffff0000, v16
	v_lshlrev_b32_e32 v58, 16, v16
	v_lshl_add_u32 v98, v96, 4, v97
	v_lshl_add_u32 v16, v132, 9, v98
	ds_read2_b64 v[20:23], v16 offset1:32
	s_ashr_i32 s62, s61, 31
	v_ashrrev_i32_e32 v33, 31, v32
	v_cmp_lt_i32_e64 s[40:41], -1, v34
	s_sub_u32 s58, s50, s42
	v_ashrrev_i32_e32 v35, 31, v132
	v_mov_b32_e32 v34, v132
	s_waitcnt lgkmcnt(0)
	v_lshlrev_b32_e32 v47, 16, v21
	v_lshlrev_b32_e32 v46, 16, v20
	v_and_b32_e32 v45, 0xffff0000, v21
	v_and_b32_e32 v44, 0xffff0000, v20
	v_lshlrev_b32_e32 v50, 16, v22
	v_lshlrev_b32_e32 v51, 16, v23
	v_and_b32_e32 v49, 0xffff0000, v23
	v_and_b32_e32 v48, 0xffff0000, v22
	s_subb_u32 s59, s51, s43
	s_movk_i32 s63, 0x2c00
	v_lshlrev_b32_e32 v63, 16, v19
	v_lshlrev_b32_e32 v62, 16, v18
	v_and_b32_e32 v61, 0xffff0000, v19
	v_and_b32_e32 v60, 0xffff0000, v18
	v_and_b32_e32 v57, 0xffff0000, v17
	v_lshlrev_b32_e32 v59, 16, v17
	v_mov_b32_e32 v248, 0x3a27c5ac
	s_waitcnt vmcnt(0)
	v_mov_b32_e32 v16, v24
	v_mov_b32_e32 v20, v9
	v_mov_b32_e32 v21, v31
	v_mov_b32_e32 v9, v30
	v_mov_b32_e32 v22, v15
	v_mov_b32_e32 v23, v29
	v_mov_b32_e32 v15, v28
	v_lshl_add_u64 v[28:29], s[42:43], 0, v[34:35]
	v_lshlrev_b64 v[30:31], 1, v[32:33]
	v_mov_b32_e32 v18, v7
	v_mov_b32_e32 v19, v1
	v_mov_b32_e32 v7, v0
	v_mov_b32_e32 v0, v13
	v_mov_b32_e32 v1, v11
	v_mov_b32_e32 v13, v10
	v_mov_b32_e32 v11, s59
	v_sub_co_u32_e32 v10, vcc, s58, v132
	v_mad_u64_u32 v[30:31], s[58:59], v28, s63, v[30:31]
	v_mov_b32_e32 v32, v31
	s_sub_u32 s42, s61, s42
	v_subb_co_u32_e32 v11, vcc, v11, v35, vcc
	v_mad_u64_u32 v[32:33], s[58:59], v29, s63, v[32:33]
	s_subb_u32 s43, s62, s43
	v_mov_b32_e32 v31, v32
	v_readlane_b32 s58, v254, 38
	v_mov_b32_e32 v33, s43
	v_sub_co_u32_e32 v32, vcc, s42, v132
	v_readlane_b32 s59, v254, 39
	s_nop 0
	v_subb_co_u32_e32 v33, vcc, v33, v35, vcc
	v_mov_b32_e32 v17, v2
	v_mov_b32_e32 v2, v25
	v_mov_b32_e32 v24, v5
	v_mov_b32_e32 v25, v27
	v_mov_b32_e32 v5, v26
	v_lshl_add_u64 v[26:27], v[10:11], 0, -1
	v_lshl_add_u64 v[30:31], s[58:59], 0, v[30:31]
	v_lshl_add_u64 v[34:35], v[32:33], 0, -1
	s_mov_b64 s[58:59], 0
	s_branch .LBB0_1112
	.p2align 6

; #define STAGE(P, BASE, br, kt) STAGET(tid_, P, BASE, br, kt)
; #define WAIT_V(n) asm volatile("s_waitcnt vmcnt(" #n ")" ::: "memory")
; #define BAR __builtin_amdgcn_s_barrier()
; template <int EPI, int K, int KL> ...
;     ...
;   if (wr == 1) BAR;
;   WAIT_V(4); BAR;
;   STAGE(SB(1, 0), Bt, bcol, 1); STAGE(SA(1, 0), A, brow, 1); STAGE(SB(1, 1), Bt, bcol + HALF, 1);
.LBB0_1183:
	s_or_b64 exec, exec, s[52:53]
	v_add_u32_e32 v2, v0, v2
	v_and_b32_e32 v2, 0xfffffc00, v2
	v_sub_u32_e32 v2, v0, v2
	v_lshrrev_b32_e32 v5, 4, v2
	v_add_u32_e32 v3, v154, v3
	v_bitop3_b32 v5, v5, v2, 32 bitop3:0x6c
	v_ashrrev_i32_e32 v2, 31, v2
	v_ashrrev_i32_e32 v3, 6, v3
	v_lshrrev_b32_e32 v2, 26, v2
	v_lshlrev_b32_e32 v6, 3, v3
	v_add_u32_e32 v2, v5, v2
	v_and_b32_e32 v6, -16, v6
	v_ashrrev_i32_e32 v2, 6, v2
	v_add_u32_e32 v12, v2, v6
	v_mul_i32_i24_e32 v2, 64, v2
	v_readlane_b32 s58, v254, 22
	v_lshlrev_b32_e32 v3, 5, v3
	v_sub_u32_e32 v2, v5, v2
	v_readlane_b32 s59, v254, 23
	s_add_u32 s52, s58, s57
	v_and_b32_e32 v3, 32, v3
	v_ashrrev_i16_sdwa v2, v207, sext(v2) dst_sel:DWORD dst_unused:UNUSED_PAD src0_sel:DWORD src1_sel:BYTE_0
	s_movk_i32 s60, 0x2c00
	s_addc_u32 s53, s59, s56
	v_add_u32_sdwa v128, v3, sext(v2) dst_sel:DWORD dst_unused:UNUSED_PAD src0_sel:DWORD src1_sel:WORD_0
	v_mad_i64_i32 v[130:131], s[56:57], v12, s60, 0
	v_mov_b64_e32 v[2:3], s[52:53]
	v_ashrrev_i32_e32 v129, 31, v128
	v_readlane_b32 s56, v254, 45
	v_ashrrev_i32_e32 v5, 31, v1
	v_mad_i64_i32 v[6:7], s[52:53], v12, s60, v[2:3]
	v_lshlrev_b64 v[8:9], 1, v[128:129]
	v_add_u32_e32 v164, s56, v0
	v_lshrrev_b32_e32 v5, 22, v5
	v_lshl_add_u64 v[6:7], v[6:7], 0, v[8:9]
	s_mov_b64 s[64:65], 0x80
	v_readfirstlane_b32 s52, v164
	v_add_u32_e32 v5, v1, v5
	v_lshl_add_u64 v[6:7], v[6:7], 0, s[64:65]
	s_mov_b32 m0, s52
	v_ashrrev_i32_e32 v5, 10, v5
	s_waitcnt vmcnt(4)
	s_barrier
; #define STAGE(P, BASE, br, kt) STAGET(tid_, P, BASE, br, kt)
; #define WAIT_V(n) asm volatile("s_waitcnt vmcnt(" #n ")" ::: "memory")
; #define BAR __builtin_amdgcn_s_barrier()
; template <int EPI, int K, int KL> ...
;     ...
;   const int wid = tid_ >> 6, lane = tid_ & 63, wr = wid >> 2, wc = wid & 3, fr = lane & 15, fq = lane >> 4;
;   f32x4 acc[2][2][4][2] = {};
;   bf16x8 At[4][2], B0[2][2], B1[2][2];
;   const int nt = KL / BK;
;   if (own_prologue) {
;     STAGE(SB(0, 0), Bt, bcol, 0); STAGE(SA(0, 0), A, brow, 0);
;     STAGE(SB(0, 1), Bt, bcol + HALF, 0); STAGE(SA(0, 1), A, brow + HALF, 0);
;   }
;   if (wr == 1) BAR;
;   WAIT_V(4); BAR;
;   STAGE(SB(1, 0), Bt, bcol, 1); STAGE(SA(1, 0), A, brow, 1); STAGE(SB(1, 1), Bt, bcol + HALF, 1);
;   WAIT_V(6); BAR;
	global_load_lds_dwordx4 v[6:7], off
	v_mul_i32_i24_e32 v6, 0x400, v5
	v_sub_u32_e32 v6, v1, v6
	v_lshrrev_b32_e32 v7, 4, v6
	v_bitop3_b32 v6, v7, v6, 32 bitop3:0x6c
	v_ashrrev_i32_e32 v10, 31, v6
	v_lshrrev_b32_e32 v10, 26, v10
	v_lshlrev_b32_e32 v7, 3, v5
	v_add_u32_e32 v10, v6, v10
	v_and_b32_e32 v7, -16, v7
	v_ashrrev_i32_e32 v11, 6, v10
	v_add_u32_e32 v13, v11, v7
	v_and_b32_e32 v7, 0xc0, v10
	v_lshlrev_b32_e32 v5, 5, v5
	v_sub_u32_e32 v6, v6, v7
	v_and_b32_e32 v5, 32, v5
	v_ashrrev_i16_sdwa v6, v207, sext(v6) dst_sel:DWORD dst_unused:UNUSED_PAD src0_sel:DWORD src1_sel:BYTE_0
	v_add_u32_sdwa v140, v5, sext(v6) dst_sel:DWORD dst_unused:UNUSED_PAD src0_sel:DWORD src1_sel:WORD_0
	v_mad_i64_i32 v[142:143], s[52:53], v13, s60, 0
	v_mad_i64_i32 v[2:3], s[52:53], v13, s60, v[2:3]
	v_ashrrev_i32_e32 v141, 31, v140
	v_add_u32_e32 v5, s56, v1
	v_lshlrev_b64 v[6:7], 1, v[140:141]
	v_readfirstlane_b32 s52, v5
	s_add_i32 s54, s54, s19
	v_lshl_add_u64 v[2:3], v[2:3], 0, v[6:7]
	s_mov_b32 m0, s52
	s_add_u32 s52, s62, s55
	v_lshl_add_u64 v[2:3], v[2:3], 0, s[64:65]
	s_addc_u32 s53, s63, s54
	global_load_lds_dwordx4 v[2:3], off
	v_mov_b64_e32 v[2:3], s[52:53]
	v_mad_i64_i32 v[10:11], s[54:55], v12, s60, v[2:3]
	v_add_u32_e32 v166, 0x8000, v157
	v_lshl_add_u64 v[10:11], v[10:11], 0, v[8:9]
	v_readfirstlane_b32 s54, v166
	s_mov_b32 m0, s54
	v_mad_i64_i32 v[2:3], s[54:55], v13, s60, v[2:3]
	v_add_u32_e32 v167, 0xa000, v157
	v_lshl_add_u64 v[10:11], v[10:11], 0, s[64:65]
	v_readfirstlane_b32 s54, v167
	global_load_lds_dwordx4 v[10:11], off
	s_mov_b32 m0, s54
	s_or_b32 s54, s18, 0x80
	s_mul_hi_i32 s55, s54, 0x2c00
	s_mulk_i32 s54, 0x2c00
	v_lshl_add_u64 v[2:3], v[2:3], 0, v[6:7]
	s_add_u32 s54, s58, s54
	v_lshl_add_u64 v[2:3], v[2:3], 0, s[64:65]
	s_addc_u32 s55, s59, s55
	global_load_lds_dwordx4 v[2:3], off
	v_mov_b64_e32 v[2:3], s[54:55]
	v_readlane_b32 s57, v254, 46
	v_mad_i64_i32 v[10:11], s[54:55], v12, s60, v[2:3]
	s_nop 0
	v_add_u32_e32 v168, s57, v0
	v_lshl_add_u64 v[10:11], v[10:11], 0, v[8:9]
	v_readfirstlane_b32 s54, v168
	s_mov_b32 m0, s54
	v_mad_i64_i32 v[2:3], s[54:55], v13, s60, v[2:3]
	v_add_u32_e32 v0, s57, v1
	v_lshl_add_u64 v[10:11], v[10:11], 0, s[64:65]
	v_lshl_add_u64 v[2:3], v[2:3], 0, v[6:7]
	v_readfirstlane_b32 s54, v0
	global_load_lds_dwordx4 v[10:11], off
	v_lshl_add_u64 v[2:3], v[2:3], 0, s[64:65]
	s_mov_b32 m0, s54
	v_and_b32_e32 v132, 15, v154
	global_load_lds_dwordx4 v[2:3], off
	v_bfe_u32 v153, v154, 4, 2
	v_lshlrev_b32_e32 v3, 2, v154
	v_lshlrev_b32_e32 v0, 4, v153
	v_lshlrev_b32_e32 v1, 6, v132
	v_and_b32_e32 v3, 32, v3
	v_bitop3_b32 v1, v0, v3, v1 bitop3:0x36
	v_readlane_b32 s54, v254, 43
	v_add_u32_e32 v11, s56, v1
	v_add_u32_e32 v12, s57, v1
	v_add_u32_e32 v5, s54, v1
	v_readlane_b32 s54, v254, 44
	v_add_u32_e32 v13, 0, v1
	v_bfe_u32 v152, v154, 6, 2
	v_add_u32_e32 v10, s54, v1
	v_lshlrev_b32_e32 v1, 6, v154
	s_movk_i32 s54, 0x3c0
	v_and_or_b32 v0, v1, s54, v0
	v_xad_u32 v3, v0, v3, 0
	v_mad_i64_i32 v[0:1], s[54:55], s18, v250, v[130:131]
	v_lshl_add_u64 v[144:145], v[0:1], 0, v[8:9]
	v_mad_i64_i32 v[0:1], s[54:55], s18, v250, v[142:143]
	v_lshl_add_u64 v[146:147], v[0:1], 0, v[6:7]
	v_mad_u64_u32 v[0:1], s[54:55], s48, v250, v[130:131]
	v_add_u32_e32 v1, s19, v1
	v_lshl_add_u64 v[148:149], v[0:1], 0, v[8:9]
	v_mad_u64_u32 v[0:1], s[54:55], s48, v250, v[142:143]
	s_waitcnt vmcnt(6)
	v_lshlrev_b32_e32 v155, 6, v4
	v_lshlrev_b32_e32 v4, 13, v4
	v_add_u32_e32 v1, s19, v1
	v_lshlrev_b32_e32 v2, 12, v152
	v_or_b32_e32 v14, 0x800, v4
	v_or_b32_e32 v15, 0x1000, v4
	v_or_b32_e32 v16, 0x1800, v4
	v_lshl_add_u64 v[150:151], v[0:1], 0, v[6:7]
	v_mov_b32_e32 v0, 0
	s_mov_b32 s19, -2
	v_add_u32_e32 v170, v5, v2
	v_add_u32_e32 v162, v13, v4
	v_add_u32_e32 v161, v3, v14
	v_add_u32_e32 v160, v3, v15
	v_add_u32_e32 v159, v3, v16
	v_add_u32_e32 v169, v10, v2
	v_add_u32_e32 v165, v11, v2
	v_add_u32_e32 v163, v12, v2
	v_mov_b32_e32 v1, v0
	v_mov_b32_e32 v2, v0
	v_mov_b32_e32 v3, v0
	v_mov_b32_e32 v4, v0
	v_mov_b32_e32 v5, v0
	v_mov_b32_e32 v6, v0
	v_mov_b32_e32 v7, v0
	v_mov_b32_e32 v8, v0
	v_mov_b32_e32 v9, v0
	v_mov_b32_e32 v10, v0
	v_mov_b32_e32 v11, v0
	v_mov_b32_e32 v12, v0
	v_mov_b32_e32 v13, v0
	v_mov_b32_e32 v14, v0
	v_mov_b32_e32 v15, v0
	v_mov_b32_e32 v16, v0
	v_mov_b32_e32 v17, v0
	v_mov_b32_e32 v18, v0
	v_mov_b32_e32 v19, v0
	v_mov_b32_e32 v20, v0
	v_mov_b32_e32 v21, v0
	v_mov_b32_e32 v22, v0
	v_mov_b32_e32 v23, v0
	v_mov_b32_e32 v24, v0
	v_mov_b32_e32 v25, v0
	v_mov_b32_e32 v26, v0
	v_mov_b32_e32 v27, v0
	v_mov_b32_e32 v28, v0
	v_mov_b32_e32 v29, v0
	v_mov_b32_e32 v30, v0
	v_mov_b32_e32 v31, v0
	v_mov_b32_e32 v32, v0
	v_mov_b32_e32 v33, v0
	v_mov_b32_e32 v34, v0
	v_mov_b32_e32 v35, v0
	v_mov_b32_e32 v36, v0
	v_mov_b32_e32 v37, v0
	v_mov_b32_e32 v38, v0
	v_mov_b32_e32 v39, v0
	v_mov_b32_e32 v40, v0
	v_mov_b32_e32 v41, v0
	v_mov_b32_e32 v42, v0
	v_mov_b32_e32 v43, v0
	v_mov_b32_e32 v44, v0
	v_mov_b32_e32 v45, v0
	v_mov_b32_e32 v46, v0
	v_mov_b32_e32 v47, v0
	v_mov_b32_e32 v48, v0
	v_mov_b32_e32 v49, v0
	v_mov_b32_e32 v50, v0
	v_mov_b32_e32 v51, v0
	v_mov_b32_e32 v52, v0
	v_mov_b32_e32 v53, v0
	v_mov_b32_e32 v54, v0
	v_mov_b32_e32 v55, v0
	v_mov_b32_e32 v56, v0
	v_mov_b32_e32 v57, v0
	v_mov_b32_e32 v58, v0
	v_mov_b32_e32 v59, v0
	v_mov_b32_e32 v60, v0
	v_mov_b32_e32 v61, v0
	v_mov_b32_e32 v62, v0
	v_mov_b32_e32 v63, v0
	v_mov_b32_e32 v64, v0
	v_mov_b32_e32 v65, v0
	v_mov_b32_e32 v66, v0
	v_mov_b32_e32 v67, v0
	v_mov_b32_e32 v68, v0
	v_mov_b32_e32 v69, v0
	v_mov_b32_e32 v70, v0
	v_mov_b32_e32 v71, v0
	v_mov_b32_e32 v72, v0
	v_mov_b32_e32 v73, v0
	v_mov_b32_e32 v74, v0
	v_mov_b32_e32 v75, v0
	v_mov_b32_e32 v76, v0
	v_mov_b32_e32 v77, v0
	v_mov_b32_e32 v78, v0
	v_mov_b32_e32 v79, v0
	v_mov_b32_e32 v80, v0
	v_mov_b32_e32 v81, v0
	v_mov_b32_e32 v82, v0
	v_mov_b32_e32 v83, v0
	v_mov_b32_e32 v84, v0
	v_mov_b32_e32 v85, v0
	v_mov_b32_e32 v86, v0
	v_mov_b32_e32 v87, v0
	v_mov_b32_e32 v88, v0
	v_mov_b32_e32 v89, v0
	v_mov_b32_e32 v90, v0
	v_mov_b32_e32 v91, v0
	v_mov_b32_e32 v92, v0
	v_mov_b32_e32 v93, v0
	v_mov_b32_e32 v94, v0
	v_mov_b32_e32 v95, v0
	v_mov_b32_e32 v96, v0
	v_mov_b32_e32 v97, v0
	v_mov_b32_e32 v98, v0
	v_mov_b32_e32 v99, v0
	v_mov_b32_e32 v100, v0
	v_mov_b32_e32 v101, v0
	v_mov_b32_e32 v102, v0
	v_mov_b32_e32 v103, v0
	v_mov_b32_e32 v104, v0
	v_mov_b32_e32 v105, v0
	v_mov_b32_e32 v106, v0
	v_mov_b32_e32 v107, v0
	v_mov_b32_e32 v108, v0
	v_mov_b32_e32 v109, v0
	v_mov_b32_e32 v110, v0
	v_mov_b32_e32 v111, v0
	v_mov_b32_e32 v112, v0
	v_mov_b32_e32 v113, v0
	v_mov_b32_e32 v114, v0
	v_mov_b32_e32 v115, v0
	v_mov_b32_e32 v116, v0
	v_mov_b32_e32 v117, v0
	v_mov_b32_e32 v118, v0
	v_mov_b32_e32 v119, v0
	v_mov_b32_e32 v120, v0
	v_mov_b32_e32 v121, v0
	v_mov_b32_e32 v122, v0
	v_mov_b32_e32 v123, v0
	v_mov_b32_e32 v124, v0
	v_mov_b32_e32 v125, v0
	v_mov_b32_e32 v126, v0
	v_mov_b32_e32 v127, v0
	.p2align 6

; #define STAGE(P, BASE, br, kt) STAGET(tid_, P, BASE, br, kt)
; #define WAIT_V(n) asm volatile("s_waitcnt vmcnt(" #n ")" ::: "memory")
; #define BAR __builtin_amdgcn_s_barrier()
; template <int EPI, int K, int KL> ...
;     ...
;   const int wid = tid_ >> 6, lane = tid_ & 63, wr = wid >> 2, wc = wid & 3, fr = lane & 15, fq = lane >> 4;
;   f32x4 acc[2][2][4][2] = {};
;   bf16x8 At[4][2], B0[2][2], B1[2][2];
;   const int nt = KL / BK;
;   if (own_prologue) {
;     STAGE(SB(0, 0), Bt, bcol, 0); STAGE(SA(0, 0), A, brow, 0);
;     STAGE(SB(0, 1), Bt, bcol + HALF, 0); STAGE(SA(0, 1), A, brow + HALF, 0);
;   }
;   if (wr == 1) BAR;
;   WAIT_V(4); BAR;
;   STAGE(SB(1, 0), Bt, bcol, 1); STAGE(SA(1, 0), A, brow, 1); STAGE(SB(1, 1), Bt, bcol + HALF, 1);
;   WAIT_V(6); BAR;
.LBB0_1203:
	s_or_b64 exec, exec, s[50:51]
	s_movk_i32 s50, 0x2c00
	v_mad_i64_i32 v[142:143], s[18:19], v13, s50, 0
	v_mad_i64_i32 v[140:141], s[18:19], v15, s50, 0
	v_readlane_b32 s50, v254, 45
	s_mov_b64 s[56:57], 0x80
	v_lshl_add_u64 v[4:5], v[4:5], 0, s[56:57]
	v_add_u32_e32 v168, s50, v12
	v_add_u32_e32 v169, 0x2000, v168
	v_readfirstlane_b32 s18, v168
	s_mov_b32 m0, s18
	v_readfirstlane_b32 s18, v169
	v_add_u32_e32 v170, 0x8000, v161
	s_waitcnt vmcnt(4)
	s_barrier
	global_load_lds_dwordx4 v[4:5], off
	v_lshl_add_u64 v[4:5], v[6:7], 0, s[56:57]
	s_mov_b32 m0, s18
	v_readfirstlane_b32 s18, v170
	v_add_u32_e32 v171, 0xa000, v161
	global_load_lds_dwordx4 v[4:5], off
	v_lshl_add_u64 v[4:5], v[8:9], 0, s[56:57]
	s_mov_b32 m0, s18
	v_readfirstlane_b32 s18, v171
	global_load_lds_dwordx4 v[4:5], off
	s_mov_b32 m0, s18
	s_add_u32 s18, s48, 0x160080
	s_addc_u32 s19, s49, 0
	v_readlane_b32 s49, v254, 46
	v_lshl_add_u64 v[4:5], v[10:11], 0, s[56:57]
	global_load_lds_dwordx4 v[4:5], off
	v_add_u32_e32 v172, s49, v12
	v_lshl_add_u64 v[4:5], s[18:19], 0, v[142:143]
	v_readfirstlane_b32 s48, v172
	v_lshl_add_u64 v[4:5], v[4:5], 0, v[0:1]
	s_mov_b32 m0, s48
	v_add_u32_e32 v174, 0x2000, v172
	global_load_lds_dwordx4 v[4:5], off
	v_lshl_add_u64 v[4:5], s[18:19], 0, v[140:141]
	v_readfirstlane_b32 s18, v174
	v_lshl_add_u64 v[4:5], v[4:5], 0, v[2:3]
	s_mov_b32 m0, s18
	v_and_b32_e32 v251, 15, v132
	global_load_lds_dwordx4 v[4:5], off
	v_bfe_u32 v252, v132, 4, 2
	v_lshlrev_b32_e32 v7, 2, v132
	v_lshlrev_b32_e32 v4, 4, v252
	v_lshlrev_b32_e32 v5, 6, v251
	v_and_b32_e32 v7, 32, v7
	v_bitop3_b32 v5, v4, v7, v5 bitop3:0x36
	v_readlane_b32 s18, v254, 43
	v_add_u32_e32 v10, s50, v5
	v_add_u32_e32 v11, s49, v5
	v_add_u32_e32 v8, s18, v5
	v_readlane_b32 s18, v254, 44
	v_add_u32_e32 v13, 0, v5
	s_and_b32 s15, s15, 7
	v_add_u32_e32 v9, s18, v5
	v_lshlrev_b32_e32 v5, 6, v132
	s_movk_i32 s18, 0x3c0
	v_and_or_b32 v4, v5, s18, v4
	v_mov_b32_e32 v17, 0x2c0000
	v_xad_u32 v7, v4, v7, 0
	v_mad_u64_u32 v[4:5], s[18:19], s15, v17, v[142:143]
	v_lshl_add_u64 v[4:5], v[4:5], 0, v[0:1]
	v_lshl_add_u64 v[144:145], s[92:93], 0, v[4:5]
	v_mad_u64_u32 v[4:5], s[18:19], s15, v17, v[140:141]
	v_lshl_add_u64 v[4:5], v[4:5], 0, v[2:3]
	v_lshl_add_u64 v[146:147], s[92:93], 0, v[4:5]
	v_mad_i64_i32 v[4:5], s[18:19], s14, v17, v[142:143]
	v_lshl_add_u64 v[0:1], v[4:5], 0, v[0:1]
	v_lshl_add_u64 v[148:149], s[92:93], 0, v[0:1]
	v_mad_i64_i32 v[0:1], s[14:15], s14, v17, v[140:141]
	v_bfe_u32 v206, v132, 6, 2
	s_waitcnt vmcnt(6)
	v_lshlrev_b32_e32 v12, 13, v14
	v_lshl_add_u64 v[0:1], v[0:1], 0, v[2:3]
	v_lshlrev_b32_e32 v6, 12, v206
	v_lshlrev_b32_e32 v134, 6, v14
	v_or_b32_e32 v14, 0x800, v12
	v_or_b32_e32 v15, 0x1000, v12
	v_or_b32_e32 v16, 0x1800, v12
	v_lshl_add_u64 v[150:151], s[92:93], 0, v[0:1]
	v_mov_b32_e32 v0, 0
	s_mov_b32 s14, -2
	v_add_u32_e32 v175, v8, v6
	v_add_u32_e32 v160, v13, v12
	v_add_u32_e32 v159, v7, v14
	v_add_u32_e32 v158, v7, v15
	v_add_u32_e32 v157, v7, v16
	v_add_u32_e32 v173, v9, v6
	v_add_u32_e32 v166, v10, v6
	v_add_u32_e32 v163, v11, v6
	v_mov_b32_e32 v1, v0
	v_mov_b32_e32 v2, v0
	v_mov_b32_e32 v3, v0
	v_mov_b32_e32 v4, v0
	v_mov_b32_e32 v5, v0
	v_mov_b32_e32 v6, v0
	v_mov_b32_e32 v7, v0
	v_mov_b32_e32 v8, v0
	v_mov_b32_e32 v9, v0
	v_mov_b32_e32 v10, v0
	v_mov_b32_e32 v11, v0
	v_mov_b32_e32 v12, v0
	v_mov_b32_e32 v13, v0
	v_mov_b32_e32 v14, v0
	v_mov_b32_e32 v15, v0
	v_mov_b32_e32 v16, v0
	v_mov_b32_e32 v17, v0
	v_mov_b32_e32 v18, v0
	v_mov_b32_e32 v19, v0
	v_mov_b32_e32 v20, v0
	v_mov_b32_e32 v21, v0
	v_mov_b32_e32 v22, v0
	v_mov_b32_e32 v23, v0
	s_waitcnt vmcnt(0)
	v_mov_b32_e32 v24, v0
	v_mov_b32_e32 v25, v0
	v_mov_b32_e32 v26, v0
	v_mov_b32_e32 v27, v0
	v_mov_b32_e32 v28, v0
	v_mov_b32_e32 v29, v0
	v_mov_b32_e32 v30, v0
	v_mov_b32_e32 v31, v0
	v_mov_b32_e32 v32, v0
	v_mov_b32_e32 v33, v0
	v_mov_b32_e32 v34, v0
	v_mov_b32_e32 v35, v0
	v_mov_b32_e32 v36, v0
	v_mov_b32_e32 v37, v0
	v_mov_b32_e32 v38, v0
	v_mov_b32_e32 v39, v0
	v_mov_b32_e32 v40, v0
	v_mov_b32_e32 v41, v0
	v_mov_b32_e32 v42, v0
	v_mov_b32_e32 v43, v0
	v_mov_b32_e32 v44, v0
	v_mov_b32_e32 v45, v0
	v_mov_b32_e32 v46, v0
	v_mov_b32_e32 v47, v0
	v_mov_b32_e32 v48, v0
	v_mov_b32_e32 v49, v0
	v_mov_b32_e32 v50, v0
	v_mov_b32_e32 v51, v0
	v_mov_b32_e32 v52, v0
	v_mov_b32_e32 v53, v0
	v_mov_b32_e32 v54, v0
	v_mov_b32_e32 v55, v0
	v_mov_b32_e32 v56, v0
	v_mov_b32_e32 v57, v0
	v_mov_b32_e32 v58, v0
	v_mov_b32_e32 v59, v0
	v_mov_b32_e32 v60, v0
	v_mov_b32_e32 v61, v0
	v_mov_b32_e32 v62, v0
	v_mov_b32_e32 v63, v0
	v_mov_b32_e32 v64, v0
	v_mov_b32_e32 v65, v0
	v_mov_b32_e32 v66, v0
	v_mov_b32_e32 v67, v0
	v_mov_b32_e32 v68, v0
	v_mov_b32_e32 v69, v0
	v_mov_b32_e32 v70, v0
	v_mov_b32_e32 v71, v0
	v_mov_b32_e32 v72, v0
	v_mov_b32_e32 v73, v0
	v_mov_b32_e32 v74, v0
	v_mov_b32_e32 v75, v0
	v_mov_b32_e32 v76, v0
	v_mov_b32_e32 v77, v0
	v_mov_b32_e32 v78, v0
	v_mov_b32_e32 v79, v0
	v_mov_b32_e32 v80, v0
	v_mov_b32_e32 v81, v0
	v_mov_b32_e32 v82, v0
	v_mov_b32_e32 v83, v0
	v_mov_b32_e32 v84, v0
	v_mov_b32_e32 v85, v0
	v_mov_b32_e32 v86, v0
	v_mov_b32_e32 v87, v0
	v_mov_b32_e32 v88, v0
	v_mov_b32_e32 v89, v0
	v_mov_b32_e32 v90, v0
	v_mov_b32_e32 v91, v0
	v_mov_b32_e32 v92, v0
	v_mov_b32_e32 v93, v0
	v_mov_b32_e32 v94, v0
	v_mov_b32_e32 v95, v0
	v_mov_b32_e32 v96, v0
	v_mov_b32_e32 v97, v0
	v_mov_b32_e32 v98, v0
	v_mov_b32_e32 v99, v0
	v_mov_b32_e32 v100, v0
	v_mov_b32_e32 v101, v0
	v_mov_b32_e32 v102, v0
	v_mov_b32_e32 v103, v0
	v_mov_b32_e32 v104, v0
	v_mov_b32_e32 v105, v0
	v_mov_b32_e32 v106, v0
	v_mov_b32_e32 v107, v0
	v_mov_b32_e32 v108, v0
	v_mov_b32_e32 v109, v0
	v_mov_b32_e32 v110, v0
	v_mov_b32_e32 v111, v0
	v_mov_b32_e32 v112, v0
	v_mov_b32_e32 v113, v0
	v_mov_b32_e32 v114, v0
	v_mov_b32_e32 v115, v0
	v_mov_b32_e32 v116, v0
	v_mov_b32_e32 v117, v0
	v_mov_b32_e32 v118, v0
	v_mov_b32_e32 v119, v0
	v_mov_b32_e32 v120, v0
	v_mov_b32_e32 v121, v0
	v_mov_b32_e32 v122, v0
	v_mov_b32_e32 v123, v0
	v_mov_b32_e32 v124, v0
	v_mov_b32_e32 v125, v0
	v_mov_b32_e32 v126, v0
	v_mov_b32_e32 v127, v0
	.p2align 6
